# FFN-in K-loop: LDS-DMA staging rebalanced to 4 loads per phase (B half-1 tiles staged one phase later), counted waits re-derived
# speedup vs baseline: 1.0063x; 1.0045x over previous
.LBB0_158:
	s_add_u32 s28, s30, 0xfffc0080
	s_addc_u32 s29, s31, -1
	s_cmp_eq_u32 s54, 12
	s_cselect_b32 s35, s23, s29
	s_cselect_b32 s34, s33, s28
	s_cselect_b32 s29, s21, s46
	s_cselect_b32 s28, s44, s45
	s_add_i32 s55, 0, 0x14000
	v_add_u32_e32 v142, s62, v167
	v_add_u32_e32 v171, s55, v167
	ds_read_b128 v[126:129], v142
	ds_read_b128 v[134:137], v142 offset:1024
	ds_read_b128 v[138:141], v142 offset:2048
	ds_read_b128 v[142:145], v142 offset:3072
	ds_read_b128 v[146:149], v171
	ds_read_b128 v[150:153], v171 offset:1024
	ds_read_b128 v[172:175], v171 offset:2048
	ds_read_b128 v[176:179], v171 offset:3072
	s_add_u32 s100, s45, 0x3ff80
	s_addc_u32 s101, s46, 0
	v_lshl_add_u64 v[188:189], s[100:101], 0, v[48:49]
	s_add_i32 m0, s41, 0x1c000
	s_nop 0
	global_load_lds_dwordx4 v[188:189], off
	v_lshl_add_u64 v[188:189], s[100:101], 0, v[158:159]
	s_add_i32 m0, s41, 0x1e000
	s_nop 0
	global_load_lds_dwordx4 v[188:189], off
	v_lshl_add_u64 v[188:189], s[30:31], 0, v[162:163]
	s_add_i32 m0, s41, 0xc000
	ds_read_b128 v[180:183], v170
	ds_read_b128 v[184:187], v170 offset:1024
	ds_read_b128 v[198:201], v170 offset:2048
	ds_read_b128 v[202:205], v170 offset:3072
	ds_read_b128 v[206:209], v170 offset:4096
	ds_read_b128 v[210:213], v170 offset:5120
	ds_read_b128 v[214:217], v170 offset:6144
	ds_read_b128 v[218:221], v170 offset:7168
	global_load_lds_dwordx4 v[188:189], off
	v_lshl_add_u64 v[188:189], s[30:31], 0, v[164:165]
	s_add_i32 m0, s41, 0xe000
	s_nop 0
	global_load_lds_dwordx4 v[188:189], off
	s_waitcnt vmcnt(8)
	s_waitcnt lgkmcnt(0)
	s_barrier
	s_setprio 1
	s_waitcnt lgkmcnt(0)
	v_mfma_f32_16x16x32_bf16 v[122:125], v[126:129], v[180:183], v[122:125]
	v_mfma_f32_16x16x32_bf16 v[114:117], v[138:141], v[180:183], v[114:117]
	v_mfma_f32_16x16x32_bf16 v[106:109], v[126:129], v[198:201], v[106:109]
	v_mfma_f32_16x16x32_bf16 v[98:101], v[138:141], v[198:201], v[98:101]
	v_mfma_f32_16x16x32_bf16 v[90:93], v[126:129], v[206:209], v[90:93]
	v_mfma_f32_16x16x32_bf16 v[82:85], v[138:141], v[206:209], v[82:85]
	v_mfma_f32_16x16x32_bf16 v[74:77], v[126:129], v[214:217], v[74:77]
	v_mfma_f32_16x16x32_bf16 v[66:69], v[138:141], v[214:217], v[66:69]
	v_mfma_f32_16x16x32_bf16 v[122:125], v[134:137], v[184:187], v[122:125]
	v_mfma_f32_16x16x32_bf16 v[114:117], v[142:145], v[184:187], v[114:117]
	v_mfma_f32_16x16x32_bf16 v[106:109], v[134:137], v[202:205], v[106:109]
	v_mfma_f32_16x16x32_bf16 v[98:101], v[142:145], v[202:205], v[98:101]
	v_mfma_f32_16x16x32_bf16 v[90:93], v[134:137], v[210:213], v[90:93]
	v_mfma_f32_16x16x32_bf16 v[82:85], v[142:145], v[210:213], v[82:85]
	v_mfma_f32_16x16x32_bf16 v[74:77], v[134:137], v[218:221], v[74:77]
	v_mfma_f32_16x16x32_bf16 v[66:69], v[142:145], v[218:221], v[66:69]
	s_setprio 0
	s_setprio 1
	v_mfma_f32_16x16x32_bf16 v[130:133], v[146:149], v[180:183], v[130:133]
	v_mfma_f32_16x16x32_bf16 v[118:121], v[172:175], v[180:183], v[118:121]
	v_mfma_f32_16x16x32_bf16 v[110:113], v[146:149], v[198:201], v[110:113]
	v_mfma_f32_16x16x32_bf16 v[102:105], v[172:175], v[198:201], v[102:105]
	v_mfma_f32_16x16x32_bf16 v[94:97], v[146:149], v[206:209], v[94:97]
	v_mfma_f32_16x16x32_bf16 v[86:89], v[172:175], v[206:209], v[86:89]
	v_mfma_f32_16x16x32_bf16 v[78:81], v[146:149], v[214:217], v[78:81]
	v_mfma_f32_16x16x32_bf16 v[70:73], v[172:175], v[214:217], v[70:73]
	v_mfma_f32_16x16x32_bf16 v[130:133], v[150:153], v[184:187], v[130:133]
	v_mfma_f32_16x16x32_bf16 v[118:121], v[176:179], v[184:187], v[118:121]
	v_mfma_f32_16x16x32_bf16 v[110:113], v[150:153], v[202:205], v[110:113]
	v_mfma_f32_16x16x32_bf16 v[102:105], v[176:179], v[202:205], v[102:105]
	v_mfma_f32_16x16x32_bf16 v[94:97], v[150:153], v[210:213], v[94:97]
	v_mfma_f32_16x16x32_bf16 v[86:89], v[176:179], v[210:213], v[86:89]
	v_mfma_f32_16x16x32_bf16 v[78:81], v[150:153], v[218:221], v[78:81]
	v_mfma_f32_16x16x32_bf16 v[70:73], v[176:179], v[218:221], v[70:73]
	s_setprio 0
	s_barrier
	s_add_i32 s56, s62, s36
	v_lshl_add_u64 v[188:189], s[28:29], 0, v[48:49]
	s_mov_b32 m0, s56
	ds_read_b128 v[180:183], v170 offset:16384
	ds_read_b128 v[184:187], v170 offset:17408
	ds_read_b128 v[198:201], v170 offset:18432
	ds_read_b128 v[202:205], v170 offset:19456
	ds_read_b128 v[206:209], v170 offset:20480
	ds_read_b128 v[210:213], v170 offset:21504
	ds_read_b128 v[214:217], v170 offset:22528
	ds_read_b128 v[218:221], v170 offset:23552
	global_load_lds_dwordx4 v[188:189], off
	s_add_i32 m0, s56, 0x2000
	s_add_u32 s68, s28, 0x40000
	v_lshl_add_u64 v[222:223], s[28:29], 0, v[158:159]
	s_addc_u32 s69, s29, 0
	s_add_i32 s55, s55, s36
	global_load_lds_dwordx4 v[222:223], off
	v_lshl_add_u64 v[238:239], s[34:35], 0, v[156:157]
	v_lshl_add_u64 v[224:225], s[34:35], 0, v[154:155]
	s_mov_b32 m0, s41
	s_nop 0
	global_load_lds_dwordx4 v[224:225], off
	s_mov_b32 m0, s48
	s_nop 0
	global_load_lds_dwordx4 v[238:239], off
	s_waitcnt vmcnt(6)
	s_waitcnt lgkmcnt(0)
	s_barrier
	s_setprio 1
	s_waitcnt lgkmcnt(0)
	v_mfma_f32_16x16x32_bf16 v[58:61], v[126:129], v[180:183], v[58:61]
	v_mfma_f32_16x16x32_bf16 v[50:53], v[138:141], v[180:183], v[50:53]
	v_mfma_f32_16x16x32_bf16 v[40:43], v[126:129], v[198:201], v[40:43]
	v_mfma_f32_16x16x32_bf16 v[32:35], v[138:141], v[198:201], v[32:35]
	v_mfma_f32_16x16x32_bf16 v[24:27], v[126:129], v[206:209], v[24:27]
	v_mfma_f32_16x16x32_bf16 v[16:19], v[138:141], v[206:209], v[16:19]
	v_mfma_f32_16x16x32_bf16 v[8:11], v[126:129], v[214:217], v[8:11]
	v_mfma_f32_16x16x32_bf16 v[0:3], v[138:141], v[214:217], v[0:3]
	v_mfma_f32_16x16x32_bf16 v[58:61], v[134:137], v[184:187], v[58:61]
	v_mfma_f32_16x16x32_bf16 v[50:53], v[142:145], v[184:187], v[50:53]
	v_mfma_f32_16x16x32_bf16 v[40:43], v[134:137], v[202:205], v[40:43]
	v_mfma_f32_16x16x32_bf16 v[32:35], v[142:145], v[202:205], v[32:35]
	v_mfma_f32_16x16x32_bf16 v[24:27], v[134:137], v[210:213], v[24:27]
	v_mfma_f32_16x16x32_bf16 v[16:19], v[142:145], v[210:213], v[16:19]
	v_mfma_f32_16x16x32_bf16 v[8:11], v[134:137], v[218:221], v[8:11]
	v_mfma_f32_16x16x32_bf16 v[0:3], v[142:145], v[218:221], v[0:3]
	s_setprio 0
	s_setprio 1
	v_mfma_f32_16x16x32_bf16 v[62:65], v[146:149], v[180:183], v[62:65]
	v_mfma_f32_16x16x32_bf16 v[54:57], v[172:175], v[180:183], v[54:57]
	v_mfma_f32_16x16x32_bf16 v[44:47], v[146:149], v[198:201], v[44:47]
	v_mfma_f32_16x16x32_bf16 v[36:39], v[172:175], v[198:201], v[36:39]
	v_mfma_f32_16x16x32_bf16 v[28:31], v[146:149], v[206:209], v[28:31]
	v_mfma_f32_16x16x32_bf16 v[20:23], v[172:175], v[206:209], v[20:23]
	v_mfma_f32_16x16x32_bf16 v[12:15], v[146:149], v[214:217], v[12:15]
	v_mfma_f32_16x16x32_bf16 v[4:7], v[172:175], v[214:217], v[4:7]
	v_mfma_f32_16x16x32_bf16 v[62:65], v[150:153], v[184:187], v[62:65]
	v_mfma_f32_16x16x32_bf16 v[54:57], v[176:179], v[184:187], v[54:57]
	v_mfma_f32_16x16x32_bf16 v[44:47], v[150:153], v[202:205], v[44:47]
	v_mfma_f32_16x16x32_bf16 v[36:39], v[176:179], v[202:205], v[36:39]
	v_mfma_f32_16x16x32_bf16 v[28:31], v[150:153], v[210:213], v[28:31]
	v_mfma_f32_16x16x32_bf16 v[20:23], v[176:179], v[210:213], v[20:23]
	v_mfma_f32_16x16x32_bf16 v[12:15], v[150:153], v[218:221], v[12:15]
	v_mfma_f32_16x16x32_bf16 v[4:7], v[176:179], v[218:221], v[4:7]
	s_setprio 0
	s_barrier
	s_add_i32 s55, 0, 0x18000
	s_add_i32 s56, 0, 0x1c000
	v_add_u32_e32 v142, s55, v167
	v_add_u32_e32 v171, s56, v167
	ds_read_b128 v[126:129], v142
	ds_read_b128 v[134:137], v142 offset:1024
	ds_read_b128 v[138:141], v142 offset:2048
	ds_read_b128 v[142:145], v142 offset:3072
	ds_read_b128 v[146:149], v171
	ds_read_b128 v[150:153], v171 offset:1024
	ds_read_b128 v[172:175], v171 offset:2048
	ds_read_b128 v[176:179], v171 offset:3072
	v_lshl_add_u64 v[240:241], s[68:69], 0, v[48:49]
	s_add_i32 m0, s41, 0x14000
	s_nop 0
	global_load_lds_dwordx4 v[240:241], off
	v_lshl_add_u64 v[240:241], s[68:69], 0, v[158:159]
	s_add_i32 m0, s41, 0x16000
	s_nop 0
	global_load_lds_dwordx4 v[240:241], off
	s_add_u32 s34, s34, 0x40000
	s_addc_u32 s35, s35, 0
	s_mov_b32 m0, s49
	v_lshl_add_u64 v[240:241], s[34:35], 0, v[154:155]
	ds_read_b128 v[180:183], v170 offset:32768
	ds_read_b128 v[184:187], v170 offset:33792
	ds_read_b128 v[198:201], v170 offset:34816
	ds_read_b128 v[202:205], v170 offset:35840
	ds_read_b128 v[206:209], v170 offset:36864
	ds_read_b128 v[210:213], v170 offset:37888
	ds_read_b128 v[214:217], v170 offset:38912
	ds_read_b128 v[218:221], v170 offset:39936
	global_load_lds_dwordx4 v[240:241], off
	v_lshl_add_u64 v[240:241], s[34:35], 0, v[156:157]
	s_mov_b32 m0, s50
	s_nop 0
	global_load_lds_dwordx4 v[240:241], off
	s_waitcnt vmcnt(8)
	s_waitcnt lgkmcnt(0)
	s_barrier
	s_setprio 1
	s_waitcnt lgkmcnt(0)
	v_mfma_f32_16x16x32_bf16 v[122:125], v[126:129], v[180:183], v[122:125]
	v_mfma_f32_16x16x32_bf16 v[114:117], v[138:141], v[180:183], v[114:117]
	v_mfma_f32_16x16x32_bf16 v[106:109], v[126:129], v[198:201], v[106:109]
	v_mfma_f32_16x16x32_bf16 v[98:101], v[138:141], v[198:201], v[98:101]
	v_mfma_f32_16x16x32_bf16 v[90:93], v[126:129], v[206:209], v[90:93]
	v_mfma_f32_16x16x32_bf16 v[82:85], v[138:141], v[206:209], v[82:85]
	v_mfma_f32_16x16x32_bf16 v[74:77], v[126:129], v[214:217], v[74:77]
	v_mfma_f32_16x16x32_bf16 v[66:69], v[138:141], v[214:217], v[66:69]
	v_mfma_f32_16x16x32_bf16 v[122:125], v[134:137], v[184:187], v[122:125]
	v_mfma_f32_16x16x32_bf16 v[114:117], v[142:145], v[184:187], v[114:117]
	v_mfma_f32_16x16x32_bf16 v[106:109], v[134:137], v[202:205], v[106:109]
	v_mfma_f32_16x16x32_bf16 v[98:101], v[142:145], v[202:205], v[98:101]
	v_mfma_f32_16x16x32_bf16 v[90:93], v[134:137], v[210:213], v[90:93]
	v_mfma_f32_16x16x32_bf16 v[82:85], v[142:145], v[210:213], v[82:85]
	v_mfma_f32_16x16x32_bf16 v[74:77], v[134:137], v[218:221], v[74:77]
	v_mfma_f32_16x16x32_bf16 v[66:69], v[142:145], v[218:221], v[66:69]
	s_setprio 0
	s_setprio 1
	v_mfma_f32_16x16x32_bf16 v[130:133], v[146:149], v[180:183], v[130:133]
	v_mfma_f32_16x16x32_bf16 v[118:121], v[172:175], v[180:183], v[118:121]
	v_mfma_f32_16x16x32_bf16 v[110:113], v[146:149], v[198:201], v[110:113]
	v_mfma_f32_16x16x32_bf16 v[102:105], v[172:175], v[198:201], v[102:105]
	v_mfma_f32_16x16x32_bf16 v[94:97], v[146:149], v[206:209], v[94:97]
	v_mfma_f32_16x16x32_bf16 v[86:89], v[172:175], v[206:209], v[86:89]
	v_mfma_f32_16x16x32_bf16 v[78:81], v[146:149], v[214:217], v[78:81]
	v_mfma_f32_16x16x32_bf16 v[70:73], v[172:175], v[214:217], v[70:73]
	v_mfma_f32_16x16x32_bf16 v[130:133], v[150:153], v[184:187], v[130:133]
	v_mfma_f32_16x16x32_bf16 v[118:121], v[176:179], v[184:187], v[118:121]
	v_mfma_f32_16x16x32_bf16 v[110:113], v[150:153], v[202:205], v[110:113]
	v_mfma_f32_16x16x32_bf16 v[102:105], v[176:179], v[202:205], v[102:105]
	v_mfma_f32_16x16x32_bf16 v[94:97], v[150:153], v[210:213], v[94:97]
	v_mfma_f32_16x16x32_bf16 v[86:89], v[176:179], v[210:213], v[86:89]
	v_mfma_f32_16x16x32_bf16 v[78:81], v[150:153], v[218:221], v[78:81]
	v_mfma_f32_16x16x32_bf16 v[70:73], v[176:179], v[218:221], v[70:73]
	s_setprio 0
	s_barrier
	s_add_i32 s34, s55, s36
	v_lshl_add_u64 v[188:189], v[188:189], 0, s[70:71]
	s_mov_b32 m0, s34
	ds_read_b128 v[180:183], v170 offset:49152
	ds_read_b128 v[184:187], v170 offset:50176
	ds_read_b128 v[198:201], v170 offset:51200
	ds_read_b128 v[202:205], v170 offset:52224
	ds_read_b128 v[206:209], v170 offset:53248
	ds_read_b128 v[210:213], v170 offset:54272
	ds_read_b128 v[214:217], v170 offset:55296
	ds_read_b128 v[218:221], v170 offset:56320
	global_load_lds_dwordx4 v[188:189], off
	s_add_i32 m0, s34, 0x2000
	s_add_u32 s28, s28, 0x40080
	v_lshl_add_u64 v[188:189], v[222:223], 0, s[70:71]
	s_addc_u32 s29, s29, 0
	s_add_i32 s34, s56, s36
	global_load_lds_dwordx4 v[188:189], off
	v_lshl_add_u64 v[188:189], v[224:225], 0, s[70:71]
	s_mov_b32 m0, s52
	s_nop 0
	global_load_lds_dwordx4 v[188:189], off
	v_lshl_add_u64 v[188:189], v[238:239], 0, s[70:71]
	s_mov_b32 m0, s53
	s_nop 0
	global_load_lds_dwordx4 v[188:189], off
	s_waitcnt vmcnt(6)
	s_waitcnt lgkmcnt(0)
	s_barrier
	s_setprio 1
	s_waitcnt lgkmcnt(0)
	v_mfma_f32_16x16x32_bf16 v[58:61], v[126:129], v[180:183], v[58:61]
	v_mfma_f32_16x16x32_bf16 v[50:53], v[138:141], v[180:183], v[50:53]
	v_mfma_f32_16x16x32_bf16 v[40:43], v[126:129], v[198:201], v[40:43]
	v_mfma_f32_16x16x32_bf16 v[32:35], v[138:141], v[198:201], v[32:35]
	v_mfma_f32_16x16x32_bf16 v[24:27], v[126:129], v[206:209], v[24:27]
	v_mfma_f32_16x16x32_bf16 v[16:19], v[138:141], v[206:209], v[16:19]
	v_mfma_f32_16x16x32_bf16 v[8:11], v[126:129], v[214:217], v[8:11]
	v_mfma_f32_16x16x32_bf16 v[0:3], v[138:141], v[214:217], v[0:3]
	v_mfma_f32_16x16x32_bf16 v[58:61], v[134:137], v[184:187], v[58:61]
	v_mfma_f32_16x16x32_bf16 v[50:53], v[142:145], v[184:187], v[50:53]
	v_mfma_f32_16x16x32_bf16 v[40:43], v[134:137], v[202:205], v[40:43]
	v_mfma_f32_16x16x32_bf16 v[32:35], v[142:145], v[202:205], v[32:35]
	v_mfma_f32_16x16x32_bf16 v[24:27], v[134:137], v[210:213], v[24:27]
	v_mfma_f32_16x16x32_bf16 v[16:19], v[142:145], v[210:213], v[16:19]
	v_mfma_f32_16x16x32_bf16 v[8:11], v[134:137], v[218:221], v[8:11]
	v_mfma_f32_16x16x32_bf16 v[0:3], v[142:145], v[218:221], v[0:3]
	s_setprio 0
	s_setprio 1
	v_mfma_f32_16x16x32_bf16 v[62:65], v[146:149], v[180:183], v[62:65]
	v_mfma_f32_16x16x32_bf16 v[54:57], v[172:175], v[180:183], v[54:57]
	v_mfma_f32_16x16x32_bf16 v[44:47], v[146:149], v[198:201], v[44:47]
	v_mfma_f32_16x16x32_bf16 v[36:39], v[172:175], v[198:201], v[36:39]
	v_mfma_f32_16x16x32_bf16 v[28:31], v[146:149], v[206:209], v[28:31]
	v_mfma_f32_16x16x32_bf16 v[20:23], v[172:175], v[206:209], v[20:23]
	v_mfma_f32_16x16x32_bf16 v[12:15], v[146:149], v[214:217], v[12:15]
	v_mfma_f32_16x16x32_bf16 v[4:7], v[172:175], v[214:217], v[4:7]
	v_mfma_f32_16x16x32_bf16 v[62:65], v[150:153], v[184:187], v[62:65]
	v_mfma_f32_16x16x32_bf16 v[54:57], v[176:179], v[184:187], v[54:57]
	v_mfma_f32_16x16x32_bf16 v[44:47], v[150:153], v[202:205], v[44:47]
	v_mfma_f32_16x16x32_bf16 v[36:39], v[176:179], v[202:205], v[36:39]
	v_mfma_f32_16x16x32_bf16 v[28:31], v[150:153], v[210:213], v[28:31]
	v_mfma_f32_16x16x32_bf16 v[20:23], v[176:179], v[210:213], v[20:23]
	v_mfma_f32_16x16x32_bf16 v[12:15], v[150:153], v[218:221], v[12:15]
	v_mfma_f32_16x16x32_bf16 v[4:7], v[176:179], v[218:221], v[4:7]
	s_setprio 0
	s_barrier
	s_add_i32 s54, s54, 2
	s_add_u32 s30, s30, 0x100
	s_addc_u32 s31, s31, 0
	s_add_u32 s45, s45, 0x100
	s_addc_u32 s46, s46, 0
	s_cmp_gt_u32 s54, 13
	s_cbranch_scc0 .LBB0_158
	s_and_b64 vcc, exec, s[18:19]
	s_cbranch_vccz .LBB0_161
	s_barrier
